# MMA segments: s_setprio 1 hoisted before the pre-MMA barrier, redundant lgkmcnt wait and mid-segment prio flips removed, post-MMA barrier signalled 4 MFMAs early with the trailing MFMAs at prio 3
# baseline (speedup 1.0000x reference)
.LBB0_182:
	s_add_u32 s57, s22, 0x100
	s_addc_u32 s59, s23, 0
	s_add_u32 s22, s24, 0x80
	v_mov_b32_e32 v0, 0
	s_addc_u32 s23, s25, 0
	s_mov_b32 s24, 0
	v_mov_b32_e32 v1, v0
	v_mov_b32_e32 v2, v0
	v_mov_b32_e32 v3, v0
	v_mov_b32_e32 v4, v0
	v_mov_b32_e32 v5, v0
	v_mov_b32_e32 v6, v0
	v_mov_b32_e32 v7, v0
	v_mov_b32_e32 v8, v0
	v_mov_b32_e32 v9, v0
	v_mov_b32_e32 v10, v0
	v_mov_b32_e32 v11, v0
	v_mov_b32_e32 v16, v0
	v_mov_b32_e32 v17, v0
	v_mov_b32_e32 v18, v0
	v_mov_b32_e32 v19, v0
	v_mov_b32_e32 v24, v0
	v_mov_b32_e32 v25, v0
	v_mov_b32_e32 v26, v0
	v_mov_b32_e32 v27, v0
	v_mov_b32_e32 v32, v0
	v_mov_b32_e32 v33, v0
	v_mov_b32_e32 v34, v0
	v_mov_b32_e32 v35, v0
	v_mov_b32_e32 v48, v0
	v_mov_b32_e32 v49, v0
	v_mov_b32_e32 v50, v0
	v_mov_b32_e32 v51, v0
	v_mov_b32_e32 v52, v0
	v_mov_b32_e32 v53, v0
	v_mov_b32_e32 v54, v0
	v_mov_b32_e32 v55, v0
	v_mov_b32_e32 v12, v0
	v_mov_b32_e32 v13, v0
	v_mov_b32_e32 v14, v0
	v_mov_b32_e32 v15, v0
	v_mov_b32_e32 v20, v0
	v_mov_b32_e32 v21, v0
	v_mov_b32_e32 v22, v0
	v_mov_b32_e32 v23, v0
	v_mov_b32_e32 v28, v0
	v_mov_b32_e32 v29, v0
	v_mov_b32_e32 v30, v0
	v_mov_b32_e32 v31, v0
	v_mov_b32_e32 v36, v0
	v_mov_b32_e32 v37, v0
	v_mov_b32_e32 v38, v0
	v_mov_b32_e32 v39, v0
	v_mov_b32_e32 v40, v0
	v_mov_b32_e32 v41, v0
	v_mov_b32_e32 v42, v0
	v_mov_b32_e32 v43, v0
	v_mov_b32_e32 v44, v0
	v_mov_b32_e32 v45, v0
	v_mov_b32_e32 v46, v0
	v_mov_b32_e32 v47, v0
	v_mov_b32_e32 v56, v0
	v_mov_b32_e32 v57, v0
	v_mov_b32_e32 v58, v0
	v_mov_b32_e32 v59, v0
	v_mov_b32_e32 v60, v0
	v_mov_b32_e32 v61, v0
	v_mov_b32_e32 v62, v0
	v_mov_b32_e32 v63, v0
	v_mov_b32_e32 v64, v0
	v_mov_b32_e32 v65, v0
	v_mov_b32_e32 v66, v0
	v_mov_b32_e32 v67, v0
	v_mov_b32_e32 v68, v0
	v_mov_b32_e32 v69, v0
	v_mov_b32_e32 v70, v0
	v_mov_b32_e32 v71, v0
	v_mov_b32_e32 v72, v0
	v_mov_b32_e32 v73, v0
	v_mov_b32_e32 v74, v0
	v_mov_b32_e32 v75, v0
	v_mov_b32_e32 v84, v0
	v_mov_b32_e32 v85, v0
	v_mov_b32_e32 v86, v0
	v_mov_b32_e32 v87, v0
	v_mov_b32_e32 v96, v0
	v_mov_b32_e32 v97, v0
	v_mov_b32_e32 v98, v0
	v_mov_b32_e32 v99, v0
	v_mov_b32_e32 v100, v0
	v_mov_b32_e32 v101, v0
	v_mov_b32_e32 v102, v0
	v_mov_b32_e32 v103, v0
	v_mov_b32_e32 v128, v0
	v_mov_b32_e32 v129, v0
	v_mov_b32_e32 v130, v0
	v_mov_b32_e32 v131, v0
	v_mov_b32_e32 v132, v0
	v_mov_b32_e32 v133, v0
	v_mov_b32_e32 v134, v0
	v_mov_b32_e32 v135, v0
	v_mov_b32_e32 v76, v0
	v_mov_b32_e32 v77, v0
	v_mov_b32_e32 v78, v0
	v_mov_b32_e32 v79, v0
	v_mov_b32_e32 v80, v0
	v_mov_b32_e32 v81, v0
	v_mov_b32_e32 v82, v0
	v_mov_b32_e32 v83, v0
	v_mov_b32_e32 v88, v0
	v_mov_b32_e32 v89, v0
	v_mov_b32_e32 v90, v0
	v_mov_b32_e32 v91, v0
	v_mov_b32_e32 v92, v0
	v_mov_b32_e32 v93, v0
	v_mov_b32_e32 v94, v0
	v_mov_b32_e32 v95, v0
	v_mov_b32_e32 v120, v0
	v_mov_b32_e32 v121, v0
	v_mov_b32_e32 v122, v0
	v_mov_b32_e32 v123, v0
	v_mov_b32_e32 v124, v0
	v_mov_b32_e32 v125, v0
	v_mov_b32_e32 v126, v0
	v_mov_b32_e32 v127, v0
	v_mov_b32_e32 v136, v0
	v_mov_b32_e32 v137, v0
	v_mov_b32_e32 v138, v0
	v_mov_b32_e32 v139, v0
	v_mov_b32_e32 v140, v0
	v_mov_b32_e32 v141, v0
	v_mov_b32_e32 v142, v0
	v_mov_b32_e32 v143, v0
	v_readlane_b32 s2, v246, 43
	s_cmp_eq_u32 s2, 0
	s_cbranch_scc1 .LBB0_183
	s_add_i32 s60, s24, 2
	s_add_u32 s2, s22, 0x80
	s_addc_u32 s3, s23, 0
	s_add_i32 s61, 0, 0x10000
	s_cmp_eq_u32 s51, s24
	s_cselect_b32 s25, s1, s3
	s_cselect_b32 s24, s0, s2
	s_cselect_b32 s3, s21, s59
	s_cselect_b32 s2, s20, s57
	s_add_i32 s62, 0, 0x14000
	v_add_u32_e32 v116, s61, v192
	v_add_u32_e32 v156, s62, v192
	ds_read_b128 v[104:107], v116
	ds_read_b128 v[108:111], v116 offset:1024
	ds_read_b128 v[112:115], v116 offset:2048
	ds_read_b128 v[116:119], v116 offset:3072
	ds_read_b128 v[144:147], v156
	ds_read_b128 v[148:151], v156 offset:1024
	ds_read_b128 v[152:155], v156 offset:2048
	ds_read_b128 v[156:159], v156 offset:3072
	v_lshl_add_u64 v[190:191], s[22:23], 0, v[188:189]
	s_add_i32 m0, s31, 0xc000
	ds_read_b128 v[160:163], v194
	ds_read_b128 v[164:167], v194 offset:1024
	ds_read_b128 v[196:199], v194 offset:2048
	ds_read_b128 v[200:203], v194 offset:3072
	ds_read_b128 v[210:213], v194 offset:4096
	ds_read_b128 v[214:217], v194 offset:5120
	ds_read_b128 v[218:221], v194 offset:6144
	ds_read_b128 v[222:225], v194 offset:7168
	global_load_lds_dwordx4 v[190:191], off
	v_lshl_add_u64 v[190:191], s[22:23], 0, v[186:187]
	s_add_i32 m0, s31, 0xe000
	s_nop 0
	global_load_lds_dwordx4 v[190:191], off
	s_waitcnt vmcnt(40)
	s_waitcnt lgkmcnt(0)
	s_setprio 1
	s_barrier
	v_mfma_f32_16x16x32_bf16 v[140:143], v[104:107], v[160:163], v[140:143]
	v_mfma_f32_16x16x32_bf16 v[140:143], v[108:111], v[164:167], v[140:143]
	v_mfma_f32_16x16x32_bf16 v[136:139], v[112:115], v[160:163], v[136:139]
	v_mfma_f32_16x16x32_bf16 v[136:139], v[116:119], v[164:167], v[136:139]
	v_mfma_f32_16x16x32_bf16 v[124:127], v[104:107], v[196:199], v[124:127]
	v_mfma_f32_16x16x32_bf16 v[124:127], v[108:111], v[200:203], v[124:127]
	v_mfma_f32_16x16x32_bf16 v[120:123], v[112:115], v[196:199], v[120:123]
	v_mfma_f32_16x16x32_bf16 v[120:123], v[116:119], v[200:203], v[120:123]
	v_mfma_f32_16x16x32_bf16 v[92:95], v[104:107], v[210:213], v[92:95]
	v_mfma_f32_16x16x32_bf16 v[92:95], v[108:111], v[214:217], v[92:95]
	v_mfma_f32_16x16x32_bf16 v[88:91], v[112:115], v[210:213], v[88:91]
	v_mfma_f32_16x16x32_bf16 v[88:91], v[116:119], v[214:217], v[88:91]
	v_mfma_f32_16x16x32_bf16 v[80:83], v[104:107], v[218:221], v[80:83]
	v_mfma_f32_16x16x32_bf16 v[80:83], v[108:111], v[222:225], v[80:83]
	v_mfma_f32_16x16x32_bf16 v[76:79], v[112:115], v[218:221], v[76:79]
	v_mfma_f32_16x16x32_bf16 v[76:79], v[116:119], v[222:225], v[76:79]
	v_mfma_f32_16x16x32_bf16 v[132:135], v[144:147], v[160:163], v[132:135]
	v_mfma_f32_16x16x32_bf16 v[132:135], v[148:151], v[164:167], v[132:135]
	v_mfma_f32_16x16x32_bf16 v[128:131], v[152:155], v[160:163], v[128:131]
	v_mfma_f32_16x16x32_bf16 v[128:131], v[156:159], v[164:167], v[128:131]
	v_mfma_f32_16x16x32_bf16 v[100:103], v[144:147], v[196:199], v[100:103]
	v_mfma_f32_16x16x32_bf16 v[100:103], v[148:151], v[200:203], v[100:103]
	v_mfma_f32_16x16x32_bf16 v[96:99], v[152:155], v[196:199], v[96:99]
	v_mfma_f32_16x16x32_bf16 v[96:99], v[156:159], v[200:203], v[96:99]
	v_mfma_f32_16x16x32_bf16 v[84:87], v[144:147], v[210:213], v[84:87]
	v_mfma_f32_16x16x32_bf16 v[84:87], v[148:151], v[214:217], v[84:87]
	v_mfma_f32_16x16x32_bf16 v[72:75], v[152:155], v[210:213], v[72:75]
	v_mfma_f32_16x16x32_bf16 v[72:75], v[156:159], v[214:217], v[72:75]
	s_setprio 3
	s_barrier
	v_mfma_f32_16x16x32_bf16 v[68:71], v[144:147], v[218:221], v[68:71]
	v_mfma_f32_16x16x32_bf16 v[68:71], v[148:151], v[222:225], v[68:71]
	v_mfma_f32_16x16x32_bf16 v[64:67], v[152:155], v[218:221], v[64:67]
	v_mfma_f32_16x16x32_bf16 v[64:67], v[156:159], v[222:225], v[64:67]
	s_setprio 0
	s_add_i32 s61, s61, s30
	v_lshl_add_u64 v[190:191], s[2:3], 0, v[174:175]
	s_mov_b32 m0, s61
	ds_read_b128 v[160:163], v194 offset:16384
	ds_read_b128 v[164:167], v194 offset:17408
	ds_read_b128 v[196:199], v194 offset:18432
	ds_read_b128 v[200:203], v194 offset:19456
	ds_read_b128 v[210:213], v194 offset:20480
	ds_read_b128 v[214:217], v194 offset:21504
	ds_read_b128 v[218:221], v194 offset:22528
	ds_read_b128 v[222:225], v194 offset:23552
	global_load_lds_dwordx4 v[190:191], off
	s_add_i32 m0, s61, 0x2000
	v_lshl_add_u64 v[226:227], s[2:3], 0, v[184:185]
	s_add_u32 s2, s2, s27
	s_addc_u32 s3, s3, 0
	s_add_i32 s61, s62, s30
	global_load_lds_dwordx4 v[226:227], off
	v_lshl_add_u64 v[228:229], s[2:3], 0, v[174:175]
	s_mov_b32 m0, s61
	v_lshl_add_u64 v[230:231], s[2:3], 0, v[184:185]
	global_load_lds_dwordx4 v[228:229], off
	s_add_i32 m0, s61, 0x2000
	v_lshl_add_u64 v[232:233], s[24:25], 0, v[168:169]
	global_load_lds_dwordx4 v[230:231], off
	s_mov_b32 m0, s31
	v_lshl_add_u64 v[234:235], s[24:25], 0, v[170:171]
	global_load_lds_dwordx4 v[232:233], off
	s_mov_b32 m0, s34
	s_nop 0
	global_load_lds_dwordx4 v[234:235], off
	s_waitcnt vmcnt(40)
	s_waitcnt lgkmcnt(0)
	s_setprio 1
	s_barrier
	v_mfma_f32_16x16x32_bf16 v[60:63], v[104:107], v[160:163], v[60:63]
	v_mfma_f32_16x16x32_bf16 v[60:63], v[108:111], v[164:167], v[60:63]
	v_mfma_f32_16x16x32_bf16 v[56:59], v[112:115], v[160:163], v[56:59]
	v_mfma_f32_16x16x32_bf16 v[56:59], v[116:119], v[164:167], v[56:59]
	v_mfma_f32_16x16x32_bf16 v[44:47], v[104:107], v[196:199], v[44:47]
	v_mfma_f32_16x16x32_bf16 v[44:47], v[108:111], v[200:203], v[44:47]
	v_mfma_f32_16x16x32_bf16 v[40:43], v[112:115], v[196:199], v[40:43]
	v_mfma_f32_16x16x32_bf16 v[40:43], v[116:119], v[200:203], v[40:43]
	v_mfma_f32_16x16x32_bf16 v[36:39], v[104:107], v[210:213], v[36:39]
	v_mfma_f32_16x16x32_bf16 v[36:39], v[108:111], v[214:217], v[36:39]
	v_mfma_f32_16x16x32_bf16 v[28:31], v[112:115], v[210:213], v[28:31]
	v_mfma_f32_16x16x32_bf16 v[28:31], v[116:119], v[214:217], v[28:31]
	v_mfma_f32_16x16x32_bf16 v[20:23], v[104:107], v[218:221], v[20:23]
	v_mfma_f32_16x16x32_bf16 v[20:23], v[108:111], v[222:225], v[20:23]
	v_mfma_f32_16x16x32_bf16 v[12:15], v[112:115], v[218:221], v[12:15]
	v_mfma_f32_16x16x32_bf16 v[12:15], v[116:119], v[222:225], v[12:15]
	v_mfma_f32_16x16x32_bf16 v[52:55], v[144:147], v[160:163], v[52:55]
	v_mfma_f32_16x16x32_bf16 v[52:55], v[148:151], v[164:167], v[52:55]
	v_mfma_f32_16x16x32_bf16 v[48:51], v[152:155], v[160:163], v[48:51]
	v_mfma_f32_16x16x32_bf16 v[48:51], v[156:159], v[164:167], v[48:51]
	v_mfma_f32_16x16x32_bf16 v[32:35], v[144:147], v[196:199], v[32:35]
	v_mfma_f32_16x16x32_bf16 v[32:35], v[148:151], v[200:203], v[32:35]
	v_mfma_f32_16x16x32_bf16 v[24:27], v[152:155], v[196:199], v[24:27]
	v_mfma_f32_16x16x32_bf16 v[24:27], v[156:159], v[200:203], v[24:27]
	v_mfma_f32_16x16x32_bf16 v[16:19], v[144:147], v[210:213], v[16:19]
	v_mfma_f32_16x16x32_bf16 v[16:19], v[148:151], v[214:217], v[16:19]
	v_mfma_f32_16x16x32_bf16 v[8:11], v[152:155], v[210:213], v[8:11]
	v_mfma_f32_16x16x32_bf16 v[8:11], v[156:159], v[214:217], v[8:11]
	s_setprio 3
	s_barrier
	v_mfma_f32_16x16x32_bf16 v[4:7], v[144:147], v[218:221], v[4:7]
	v_mfma_f32_16x16x32_bf16 v[4:7], v[148:151], v[222:225], v[4:7]
	v_mfma_f32_16x16x32_bf16 v[0:3], v[152:155], v[218:221], v[0:3]
	v_mfma_f32_16x16x32_bf16 v[0:3], v[156:159], v[222:225], v[0:3]
	s_setprio 0
	s_add_i32 s61, 0, 0x18000
	s_add_i32 s62, 0, 0x1c000
	v_add_u32_e32 v116, s61, v192
	v_add_u32_e32 v156, s62, v192
	ds_read_b128 v[104:107], v116
	ds_read_b128 v[108:111], v116 offset:1024
	ds_read_b128 v[112:115], v116 offset:2048
	ds_read_b128 v[116:119], v116 offset:3072
	ds_read_b128 v[144:147], v156
	ds_read_b128 v[148:151], v156 offset:1024
	ds_read_b128 v[152:155], v156 offset:2048
	ds_read_b128 v[156:159], v156 offset:3072
	s_add_u32 s2, s24, s78
	s_addc_u32 s3, s25, 0
	s_mov_b32 m0, s35
	v_lshl_add_u64 v[236:237], s[2:3], 0, v[168:169]
	ds_read_b128 v[160:163], v194 offset:32768
	ds_read_b128 v[164:167], v194 offset:33792
	ds_read_b128 v[196:199], v194 offset:34816
	ds_read_b128 v[200:203], v194 offset:35840
	ds_read_b128 v[210:213], v194 offset:36864
	ds_read_b128 v[214:217], v194 offset:37888
	ds_read_b128 v[218:221], v194 offset:38912
	ds_read_b128 v[222:225], v194 offset:39936
	global_load_lds_dwordx4 v[236:237], off
	v_lshl_add_u64 v[236:237], s[2:3], 0, v[170:171]
	s_mov_b32 m0, s36
	s_nop 0
	global_load_lds_dwordx4 v[236:237], off
	s_waitcnt vmcnt(8)
	s_waitcnt lgkmcnt(0)
	s_setprio 1
	s_barrier
	v_mfma_f32_16x16x32_bf16 v[140:143], v[104:107], v[160:163], v[140:143]
	v_mfma_f32_16x16x32_bf16 v[140:143], v[108:111], v[164:167], v[140:143]
	v_mfma_f32_16x16x32_bf16 v[136:139], v[112:115], v[160:163], v[136:139]
	v_mfma_f32_16x16x32_bf16 v[136:139], v[116:119], v[164:167], v[136:139]
	v_mfma_f32_16x16x32_bf16 v[124:127], v[104:107], v[196:199], v[124:127]
	v_mfma_f32_16x16x32_bf16 v[124:127], v[108:111], v[200:203], v[124:127]
	v_mfma_f32_16x16x32_bf16 v[120:123], v[112:115], v[196:199], v[120:123]
	v_mfma_f32_16x16x32_bf16 v[120:123], v[116:119], v[200:203], v[120:123]
	v_mfma_f32_16x16x32_bf16 v[92:95], v[104:107], v[210:213], v[92:95]
	v_mfma_f32_16x16x32_bf16 v[92:95], v[108:111], v[214:217], v[92:95]
	v_mfma_f32_16x16x32_bf16 v[88:91], v[112:115], v[210:213], v[88:91]
	v_mfma_f32_16x16x32_bf16 v[88:91], v[116:119], v[214:217], v[88:91]
	v_mfma_f32_16x16x32_bf16 v[80:83], v[104:107], v[218:221], v[80:83]
	v_mfma_f32_16x16x32_bf16 v[80:83], v[108:111], v[222:225], v[80:83]
	v_mfma_f32_16x16x32_bf16 v[76:79], v[112:115], v[218:221], v[76:79]
	v_mfma_f32_16x16x32_bf16 v[76:79], v[116:119], v[222:225], v[76:79]
	v_mfma_f32_16x16x32_bf16 v[132:135], v[144:147], v[160:163], v[132:135]
	v_mfma_f32_16x16x32_bf16 v[132:135], v[148:151], v[164:167], v[132:135]
	v_mfma_f32_16x16x32_bf16 v[128:131], v[152:155], v[160:163], v[128:131]
	v_mfma_f32_16x16x32_bf16 v[128:131], v[156:159], v[164:167], v[128:131]
	v_mfma_f32_16x16x32_bf16 v[100:103], v[144:147], v[196:199], v[100:103]
	v_mfma_f32_16x16x32_bf16 v[100:103], v[148:151], v[200:203], v[100:103]
	v_mfma_f32_16x16x32_bf16 v[96:99], v[152:155], v[196:199], v[96:99]
	v_mfma_f32_16x16x32_bf16 v[96:99], v[156:159], v[200:203], v[96:99]
	v_mfma_f32_16x16x32_bf16 v[84:87], v[144:147], v[210:213], v[84:87]
	v_mfma_f32_16x16x32_bf16 v[84:87], v[148:151], v[214:217], v[84:87]
	v_mfma_f32_16x16x32_bf16 v[72:75], v[152:155], v[210:213], v[72:75]
	v_mfma_f32_16x16x32_bf16 v[72:75], v[156:159], v[214:217], v[72:75]
	s_setprio 3
	s_barrier
	v_mfma_f32_16x16x32_bf16 v[68:71], v[144:147], v[218:221], v[68:71]
	v_mfma_f32_16x16x32_bf16 v[68:71], v[148:151], v[222:225], v[68:71]
	v_mfma_f32_16x16x32_bf16 v[64:67], v[152:155], v[218:221], v[64:67]
	v_mfma_f32_16x16x32_bf16 v[64:67], v[156:159], v[222:225], v[64:67]
	s_setprio 0
	s_add_i32 s2, s61, s30
	v_lshl_add_u64 v[190:191], v[190:191], 0, s[82:83]
	s_mov_b32 m0, s2
	ds_read_b128 v[160:163], v194 offset:49152
	ds_read_b128 v[164:167], v194 offset:50176
	ds_read_b128 v[196:199], v194 offset:51200
	ds_read_b128 v[200:203], v194 offset:52224
	ds_read_b128 v[210:213], v194 offset:53248
	ds_read_b128 v[214:217], v194 offset:54272
	ds_read_b128 v[218:221], v194 offset:55296
	ds_read_b128 v[222:225], v194 offset:56320
	global_load_lds_dwordx4 v[190:191], off
	v_lshl_add_u64 v[190:191], v[226:227], 0, s[82:83]
	s_add_i32 m0, s2, 0x2000
	s_add_i32 s2, s62, s30
	global_load_lds_dwordx4 v[190:191], off
	v_lshl_add_u64 v[190:191], v[228:229], 0, s[82:83]
	s_mov_b32 m0, s2
	s_nop 0
	global_load_lds_dwordx4 v[190:191], off
	v_lshl_add_u64 v[190:191], v[230:231], 0, s[82:83]
	s_add_i32 m0, s2, 0x2000
	s_nop 0
	global_load_lds_dwordx4 v[190:191], off
	v_lshl_add_u64 v[190:191], v[232:233], 0, s[82:83]
	s_mov_b32 m0, s47
	s_nop 0
	global_load_lds_dwordx4 v[190:191], off
	v_lshl_add_u64 v[190:191], v[234:235], 0, s[82:83]
	s_mov_b32 m0, s50
	s_nop 0
	global_load_lds_dwordx4 v[190:191], off
	s_waitcnt vmcnt(8)
	s_waitcnt lgkmcnt(0)
	s_setprio 1
	s_barrier
	v_mfma_f32_16x16x32_bf16 v[60:63], v[104:107], v[160:163], v[60:63]
	v_mfma_f32_16x16x32_bf16 v[60:63], v[108:111], v[164:167], v[60:63]
	v_mfma_f32_16x16x32_bf16 v[56:59], v[112:115], v[160:163], v[56:59]
	v_mfma_f32_16x16x32_bf16 v[56:59], v[116:119], v[164:167], v[56:59]
	v_mfma_f32_16x16x32_bf16 v[44:47], v[104:107], v[196:199], v[44:47]
	v_mfma_f32_16x16x32_bf16 v[44:47], v[108:111], v[200:203], v[44:47]
	v_mfma_f32_16x16x32_bf16 v[40:43], v[112:115], v[196:199], v[40:43]
	v_mfma_f32_16x16x32_bf16 v[40:43], v[116:119], v[200:203], v[40:43]
	v_mfma_f32_16x16x32_bf16 v[36:39], v[104:107], v[210:213], v[36:39]
	v_mfma_f32_16x16x32_bf16 v[36:39], v[108:111], v[214:217], v[36:39]
	v_mfma_f32_16x16x32_bf16 v[28:31], v[112:115], v[210:213], v[28:31]
	v_mfma_f32_16x16x32_bf16 v[28:31], v[116:119], v[214:217], v[28:31]
	v_mfma_f32_16x16x32_bf16 v[20:23], v[104:107], v[218:221], v[20:23]
	v_mfma_f32_16x16x32_bf16 v[20:23], v[108:111], v[222:225], v[20:23]
	v_mfma_f32_16x16x32_bf16 v[12:15], v[112:115], v[218:221], v[12:15]
	v_mfma_f32_16x16x32_bf16 v[12:15], v[116:119], v[222:225], v[12:15]
	v_mfma_f32_16x16x32_bf16 v[52:55], v[144:147], v[160:163], v[52:55]
	v_mfma_f32_16x16x32_bf16 v[52:55], v[148:151], v[164:167], v[52:55]
	v_mfma_f32_16x16x32_bf16 v[48:51], v[152:155], v[160:163], v[48:51]
	v_mfma_f32_16x16x32_bf16 v[48:51], v[156:159], v[164:167], v[48:51]
	v_mfma_f32_16x16x32_bf16 v[32:35], v[144:147], v[196:199], v[32:35]
	v_mfma_f32_16x16x32_bf16 v[32:35], v[148:151], v[200:203], v[32:35]
	v_mfma_f32_16x16x32_bf16 v[24:27], v[152:155], v[196:199], v[24:27]
	v_mfma_f32_16x16x32_bf16 v[24:27], v[156:159], v[200:203], v[24:27]
	v_mfma_f32_16x16x32_bf16 v[16:19], v[144:147], v[210:213], v[16:19]
	v_mfma_f32_16x16x32_bf16 v[16:19], v[148:151], v[214:217], v[16:19]
	v_mfma_f32_16x16x32_bf16 v[8:11], v[152:155], v[210:213], v[8:11]
	v_mfma_f32_16x16x32_bf16 v[8:11], v[156:159], v[214:217], v[8:11]
	s_setprio 3
	s_barrier
	v_mfma_f32_16x16x32_bf16 v[4:7], v[144:147], v[218:221], v[4:7]
	v_mfma_f32_16x16x32_bf16 v[4:7], v[148:151], v[222:225], v[4:7]
	v_mfma_f32_16x16x32_bf16 v[0:3], v[152:155], v[218:221], v[0:3]
	v_mfma_f32_16x16x32_bf16 v[0:3], v[156:159], v[222:225], v[0:3]
	s_setprio 0
	s_add_u32 s57, s57, 0x100
	s_addc_u32 s59, s59, 0
	s_add_u32 s22, s22, 0x100
	s_addc_u32 s23, s23, 0
	s_cmp_ge_u32 s60, s46
	s_mov_b32 s24, s60
	s_cbranch_scc1 .Lexit_183
.LBB0_183:
	s_add_i32 s60, s24, 2
	s_add_u32 s2, s22, 0x80
	s_addc_u32 s3, s23, 0
	s_add_i32 s61, 0, 0x10000
	s_cmp_eq_u32 s51, s24
	s_cselect_b32 s25, s1, s3
	s_cselect_b32 s24, s0, s2
	s_cselect_b32 s3, s21, s59
	s_cselect_b32 s2, s20, s57
	s_add_i32 s62, 0, 0x14000
	v_add_u32_e32 v116, s61, v192
	v_add_u32_e32 v156, s62, v192
	ds_read_b128 v[104:107], v116
	ds_read_b128 v[108:111], v116 offset:1024
	ds_read_b128 v[112:115], v116 offset:2048
	ds_read_b128 v[116:119], v116 offset:3072
	ds_read_b128 v[144:147], v156
	ds_read_b128 v[148:151], v156 offset:1024
	ds_read_b128 v[152:155], v156 offset:2048
	ds_read_b128 v[156:159], v156 offset:3072
	v_lshl_add_u64 v[190:191], s[22:23], 0, v[188:189]
	s_add_i32 m0, s31, 0xc000
	ds_read_b128 v[160:163], v194
	ds_read_b128 v[164:167], v194 offset:1024
	ds_read_b128 v[196:199], v194 offset:2048
	ds_read_b128 v[200:203], v194 offset:3072
	ds_read_b128 v[210:213], v194 offset:4096
	ds_read_b128 v[214:217], v194 offset:5120
	ds_read_b128 v[218:221], v194 offset:6144
	ds_read_b128 v[222:225], v194 offset:7168
	global_load_lds_dwordx4 v[190:191], off
	v_lshl_add_u64 v[190:191], s[22:23], 0, v[186:187]
	s_add_i32 m0, s31, 0xe000
	s_nop 0
	global_load_lds_dwordx4 v[190:191], off
	s_waitcnt vmcnt(8)
	s_waitcnt lgkmcnt(0)
	s_setprio 1
	s_barrier
	v_mfma_f32_16x16x32_bf16 v[140:143], v[104:107], v[160:163], v[140:143]
	v_mfma_f32_16x16x32_bf16 v[140:143], v[108:111], v[164:167], v[140:143]
	v_mfma_f32_16x16x32_bf16 v[136:139], v[112:115], v[160:163], v[136:139]
	v_mfma_f32_16x16x32_bf16 v[136:139], v[116:119], v[164:167], v[136:139]
	v_mfma_f32_16x16x32_bf16 v[124:127], v[104:107], v[196:199], v[124:127]
	v_mfma_f32_16x16x32_bf16 v[124:127], v[108:111], v[200:203], v[124:127]
	v_mfma_f32_16x16x32_bf16 v[120:123], v[112:115], v[196:199], v[120:123]
	v_mfma_f32_16x16x32_bf16 v[120:123], v[116:119], v[200:203], v[120:123]
	v_mfma_f32_16x16x32_bf16 v[92:95], v[104:107], v[210:213], v[92:95]
	v_mfma_f32_16x16x32_bf16 v[92:95], v[108:111], v[214:217], v[92:95]
	v_mfma_f32_16x16x32_bf16 v[88:91], v[112:115], v[210:213], v[88:91]
	v_mfma_f32_16x16x32_bf16 v[88:91], v[116:119], v[214:217], v[88:91]
	v_mfma_f32_16x16x32_bf16 v[80:83], v[104:107], v[218:221], v[80:83]
	v_mfma_f32_16x16x32_bf16 v[80:83], v[108:111], v[222:225], v[80:83]
	v_mfma_f32_16x16x32_bf16 v[76:79], v[112:115], v[218:221], v[76:79]
	v_mfma_f32_16x16x32_bf16 v[76:79], v[116:119], v[222:225], v[76:79]
	v_mfma_f32_16x16x32_bf16 v[132:135], v[144:147], v[160:163], v[132:135]
	v_mfma_f32_16x16x32_bf16 v[132:135], v[148:151], v[164:167], v[132:135]
	v_mfma_f32_16x16x32_bf16 v[128:131], v[152:155], v[160:163], v[128:131]
	v_mfma_f32_16x16x32_bf16 v[128:131], v[156:159], v[164:167], v[128:131]
	v_mfma_f32_16x16x32_bf16 v[100:103], v[144:147], v[196:199], v[100:103]
	v_mfma_f32_16x16x32_bf16 v[100:103], v[148:151], v[200:203], v[100:103]
	v_mfma_f32_16x16x32_bf16 v[96:99], v[152:155], v[196:199], v[96:99]
	v_mfma_f32_16x16x32_bf16 v[96:99], v[156:159], v[200:203], v[96:99]
	v_mfma_f32_16x16x32_bf16 v[84:87], v[144:147], v[210:213], v[84:87]
	v_mfma_f32_16x16x32_bf16 v[84:87], v[148:151], v[214:217], v[84:87]
	v_mfma_f32_16x16x32_bf16 v[72:75], v[152:155], v[210:213], v[72:75]
	v_mfma_f32_16x16x32_bf16 v[72:75], v[156:159], v[214:217], v[72:75]
	s_setprio 3
	s_barrier
	v_mfma_f32_16x16x32_bf16 v[68:71], v[144:147], v[218:221], v[68:71]
	v_mfma_f32_16x16x32_bf16 v[68:71], v[148:151], v[222:225], v[68:71]
	v_mfma_f32_16x16x32_bf16 v[64:67], v[152:155], v[218:221], v[64:67]
	v_mfma_f32_16x16x32_bf16 v[64:67], v[156:159], v[222:225], v[64:67]
	s_setprio 0
	s_add_i32 s61, s61, s30
	v_lshl_add_u64 v[190:191], s[2:3], 0, v[174:175]
	s_mov_b32 m0, s61
	ds_read_b128 v[160:163], v194 offset:16384
	ds_read_b128 v[164:167], v194 offset:17408
	ds_read_b128 v[196:199], v194 offset:18432
	ds_read_b128 v[200:203], v194 offset:19456
	ds_read_b128 v[210:213], v194 offset:20480
	ds_read_b128 v[214:217], v194 offset:21504
	ds_read_b128 v[218:221], v194 offset:22528
	ds_read_b128 v[222:225], v194 offset:23552
	global_load_lds_dwordx4 v[190:191], off
	s_add_i32 m0, s61, 0x2000
	v_lshl_add_u64 v[226:227], s[2:3], 0, v[184:185]
	s_add_u32 s2, s2, s27
	s_addc_u32 s3, s3, 0
	s_add_i32 s61, s62, s30
	global_load_lds_dwordx4 v[226:227], off
	v_lshl_add_u64 v[228:229], s[2:3], 0, v[174:175]
	s_mov_b32 m0, s61
	v_lshl_add_u64 v[230:231], s[2:3], 0, v[184:185]
	global_load_lds_dwordx4 v[228:229], off
	s_add_i32 m0, s61, 0x2000
	v_lshl_add_u64 v[232:233], s[24:25], 0, v[168:169]
	global_load_lds_dwordx4 v[230:231], off
	s_mov_b32 m0, s31
	v_lshl_add_u64 v[234:235], s[24:25], 0, v[170:171]
	global_load_lds_dwordx4 v[232:233], off
	s_mov_b32 m0, s34
	s_nop 0
	global_load_lds_dwordx4 v[234:235], off
	s_waitcnt vmcnt(8)
	s_waitcnt lgkmcnt(0)
	s_setprio 1
	s_barrier
	v_mfma_f32_16x16x32_bf16 v[60:63], v[104:107], v[160:163], v[60:63]
	v_mfma_f32_16x16x32_bf16 v[60:63], v[108:111], v[164:167], v[60:63]
	v_mfma_f32_16x16x32_bf16 v[56:59], v[112:115], v[160:163], v[56:59]
	v_mfma_f32_16x16x32_bf16 v[56:59], v[116:119], v[164:167], v[56:59]
	v_mfma_f32_16x16x32_bf16 v[44:47], v[104:107], v[196:199], v[44:47]
	v_mfma_f32_16x16x32_bf16 v[44:47], v[108:111], v[200:203], v[44:47]
	v_mfma_f32_16x16x32_bf16 v[40:43], v[112:115], v[196:199], v[40:43]
	v_mfma_f32_16x16x32_bf16 v[40:43], v[116:119], v[200:203], v[40:43]
	v_mfma_f32_16x16x32_bf16 v[36:39], v[104:107], v[210:213], v[36:39]
	v_mfma_f32_16x16x32_bf16 v[36:39], v[108:111], v[214:217], v[36:39]
	v_mfma_f32_16x16x32_bf16 v[28:31], v[112:115], v[210:213], v[28:31]
	v_mfma_f32_16x16x32_bf16 v[28:31], v[116:119], v[214:217], v[28:31]
	v_mfma_f32_16x16x32_bf16 v[20:23], v[104:107], v[218:221], v[20:23]
	v_mfma_f32_16x16x32_bf16 v[20:23], v[108:111], v[222:225], v[20:23]
	v_mfma_f32_16x16x32_bf16 v[12:15], v[112:115], v[218:221], v[12:15]
	v_mfma_f32_16x16x32_bf16 v[12:15], v[116:119], v[222:225], v[12:15]
	v_mfma_f32_16x16x32_bf16 v[52:55], v[144:147], v[160:163], v[52:55]
	v_mfma_f32_16x16x32_bf16 v[52:55], v[148:151], v[164:167], v[52:55]
	v_mfma_f32_16x16x32_bf16 v[48:51], v[152:155], v[160:163], v[48:51]
	v_mfma_f32_16x16x32_bf16 v[48:51], v[156:159], v[164:167], v[48:51]
	v_mfma_f32_16x16x32_bf16 v[32:35], v[144:147], v[196:199], v[32:35]
	v_mfma_f32_16x16x32_bf16 v[32:35], v[148:151], v[200:203], v[32:35]
	v_mfma_f32_16x16x32_bf16 v[24:27], v[152:155], v[196:199], v[24:27]
	v_mfma_f32_16x16x32_bf16 v[24:27], v[156:159], v[200:203], v[24:27]
	v_mfma_f32_16x16x32_bf16 v[16:19], v[144:147], v[210:213], v[16:19]
	v_mfma_f32_16x16x32_bf16 v[16:19], v[148:151], v[214:217], v[16:19]
	v_mfma_f32_16x16x32_bf16 v[8:11], v[152:155], v[210:213], v[8:11]
	v_mfma_f32_16x16x32_bf16 v[8:11], v[156:159], v[214:217], v[8:11]
	s_setprio 3
	s_barrier
	v_mfma_f32_16x16x32_bf16 v[4:7], v[144:147], v[218:221], v[4:7]
	v_mfma_f32_16x16x32_bf16 v[4:7], v[148:151], v[222:225], v[4:7]
	v_mfma_f32_16x16x32_bf16 v[0:3], v[152:155], v[218:221], v[0:3]
	v_mfma_f32_16x16x32_bf16 v[0:3], v[156:159], v[222:225], v[0:3]
	s_setprio 0
	s_add_i32 s61, 0, 0x18000
	s_add_i32 s62, 0, 0x1c000
	v_add_u32_e32 v116, s61, v192
	v_add_u32_e32 v156, s62, v192
	ds_read_b128 v[104:107], v116
	ds_read_b128 v[108:111], v116 offset:1024
	ds_read_b128 v[112:115], v116 offset:2048
	ds_read_b128 v[116:119], v116 offset:3072
	ds_read_b128 v[144:147], v156
	ds_read_b128 v[148:151], v156 offset:1024
	ds_read_b128 v[152:155], v156 offset:2048
	ds_read_b128 v[156:159], v156 offset:3072
	s_add_u32 s2, s24, s78
	s_addc_u32 s3, s25, 0
	s_mov_b32 m0, s35
	v_lshl_add_u64 v[236:237], s[2:3], 0, v[168:169]
	ds_read_b128 v[160:163], v194 offset:32768
	ds_read_b128 v[164:167], v194 offset:33792
	ds_read_b128 v[196:199], v194 offset:34816
	ds_read_b128 v[200:203], v194 offset:35840
	ds_read_b128 v[210:213], v194 offset:36864
	ds_read_b128 v[214:217], v194 offset:37888
	ds_read_b128 v[218:221], v194 offset:38912
	ds_read_b128 v[222:225], v194 offset:39936
	global_load_lds_dwordx4 v[236:237], off
	v_lshl_add_u64 v[236:237], s[2:3], 0, v[170:171]
	s_mov_b32 m0, s36
	s_nop 0
	global_load_lds_dwordx4 v[236:237], off
	s_waitcnt vmcnt(8)
	s_waitcnt lgkmcnt(0)
	s_setprio 1
	s_barrier
	v_mfma_f32_16x16x32_bf16 v[140:143], v[104:107], v[160:163], v[140:143]
	v_mfma_f32_16x16x32_bf16 v[140:143], v[108:111], v[164:167], v[140:143]
	v_mfma_f32_16x16x32_bf16 v[136:139], v[112:115], v[160:163], v[136:139]
	v_mfma_f32_16x16x32_bf16 v[136:139], v[116:119], v[164:167], v[136:139]
	v_mfma_f32_16x16x32_bf16 v[124:127], v[104:107], v[196:199], v[124:127]
	v_mfma_f32_16x16x32_bf16 v[124:127], v[108:111], v[200:203], v[124:127]
	v_mfma_f32_16x16x32_bf16 v[120:123], v[112:115], v[196:199], v[120:123]
	v_mfma_f32_16x16x32_bf16 v[120:123], v[116:119], v[200:203], v[120:123]
	v_mfma_f32_16x16x32_bf16 v[92:95], v[104:107], v[210:213], v[92:95]
	v_mfma_f32_16x16x32_bf16 v[92:95], v[108:111], v[214:217], v[92:95]
	v_mfma_f32_16x16x32_bf16 v[88:91], v[112:115], v[210:213], v[88:91]
	v_mfma_f32_16x16x32_bf16 v[88:91], v[116:119], v[214:217], v[88:91]
	v_mfma_f32_16x16x32_bf16 v[80:83], v[104:107], v[218:221], v[80:83]
	v_mfma_f32_16x16x32_bf16 v[80:83], v[108:111], v[222:225], v[80:83]
	v_mfma_f32_16x16x32_bf16 v[76:79], v[112:115], v[218:221], v[76:79]
	v_mfma_f32_16x16x32_bf16 v[76:79], v[116:119], v[222:225], v[76:79]
	v_mfma_f32_16x16x32_bf16 v[132:135], v[144:147], v[160:163], v[132:135]
	v_mfma_f32_16x16x32_bf16 v[132:135], v[148:151], v[164:167], v[132:135]
	v_mfma_f32_16x16x32_bf16 v[128:131], v[152:155], v[160:163], v[128:131]
	v_mfma_f32_16x16x32_bf16 v[128:131], v[156:159], v[164:167], v[128:131]
	v_mfma_f32_16x16x32_bf16 v[100:103], v[144:147], v[196:199], v[100:103]
	v_mfma_f32_16x16x32_bf16 v[100:103], v[148:151], v[200:203], v[100:103]
	v_mfma_f32_16x16x32_bf16 v[96:99], v[152:155], v[196:199], v[96:99]
	v_mfma_f32_16x16x32_bf16 v[96:99], v[156:159], v[200:203], v[96:99]
	v_mfma_f32_16x16x32_bf16 v[84:87], v[144:147], v[210:213], v[84:87]
	v_mfma_f32_16x16x32_bf16 v[84:87], v[148:151], v[214:217], v[84:87]
	v_mfma_f32_16x16x32_bf16 v[72:75], v[152:155], v[210:213], v[72:75]
	v_mfma_f32_16x16x32_bf16 v[72:75], v[156:159], v[214:217], v[72:75]
	s_setprio 3
	s_barrier
	v_mfma_f32_16x16x32_bf16 v[68:71], v[144:147], v[218:221], v[68:71]
	v_mfma_f32_16x16x32_bf16 v[68:71], v[148:151], v[222:225], v[68:71]
	v_mfma_f32_16x16x32_bf16 v[64:67], v[152:155], v[218:221], v[64:67]
	v_mfma_f32_16x16x32_bf16 v[64:67], v[156:159], v[222:225], v[64:67]
	s_setprio 0
	s_add_i32 s2, s61, s30
	v_lshl_add_u64 v[190:191], v[190:191], 0, s[82:83]
	s_mov_b32 m0, s2
	ds_read_b128 v[160:163], v194 offset:49152
	ds_read_b128 v[164:167], v194 offset:50176
	ds_read_b128 v[196:199], v194 offset:51200
	ds_read_b128 v[200:203], v194 offset:52224
	ds_read_b128 v[210:213], v194 offset:53248
	ds_read_b128 v[214:217], v194 offset:54272
	ds_read_b128 v[218:221], v194 offset:55296
	ds_read_b128 v[222:225], v194 offset:56320
	global_load_lds_dwordx4 v[190:191], off
	v_lshl_add_u64 v[190:191], v[226:227], 0, s[82:83]
	s_add_i32 m0, s2, 0x2000
	s_add_i32 s2, s62, s30
	global_load_lds_dwordx4 v[190:191], off
	v_lshl_add_u64 v[190:191], v[228:229], 0, s[82:83]
	s_mov_b32 m0, s2
	s_nop 0
	global_load_lds_dwordx4 v[190:191], off
	v_lshl_add_u64 v[190:191], v[230:231], 0, s[82:83]
	s_add_i32 m0, s2, 0x2000
	s_nop 0
	global_load_lds_dwordx4 v[190:191], off
	v_lshl_add_u64 v[190:191], v[232:233], 0, s[82:83]
	s_mov_b32 m0, s47
	s_nop 0
	global_load_lds_dwordx4 v[190:191], off
	v_lshl_add_u64 v[190:191], v[234:235], 0, s[82:83]
	s_mov_b32 m0, s50
	s_nop 0
	global_load_lds_dwordx4 v[190:191], off
	s_waitcnt vmcnt(8)
	s_waitcnt lgkmcnt(0)
	s_setprio 1
	s_barrier
	v_mfma_f32_16x16x32_bf16 v[60:63], v[104:107], v[160:163], v[60:63]
	v_mfma_f32_16x16x32_bf16 v[60:63], v[108:111], v[164:167], v[60:63]
	v_mfma_f32_16x16x32_bf16 v[56:59], v[112:115], v[160:163], v[56:59]
	v_mfma_f32_16x16x32_bf16 v[56:59], v[116:119], v[164:167], v[56:59]
	v_mfma_f32_16x16x32_bf16 v[44:47], v[104:107], v[196:199], v[44:47]
	v_mfma_f32_16x16x32_bf16 v[44:47], v[108:111], v[200:203], v[44:47]
	v_mfma_f32_16x16x32_bf16 v[40:43], v[112:115], v[196:199], v[40:43]
	v_mfma_f32_16x16x32_bf16 v[40:43], v[116:119], v[200:203], v[40:43]
	v_mfma_f32_16x16x32_bf16 v[36:39], v[104:107], v[210:213], v[36:39]
	v_mfma_f32_16x16x32_bf16 v[36:39], v[108:111], v[214:217], v[36:39]
	v_mfma_f32_16x16x32_bf16 v[28:31], v[112:115], v[210:213], v[28:31]
	v_mfma_f32_16x16x32_bf16 v[28:31], v[116:119], v[214:217], v[28:31]
	v_mfma_f32_16x16x32_bf16 v[20:23], v[104:107], v[218:221], v[20:23]
	v_mfma_f32_16x16x32_bf16 v[20:23], v[108:111], v[222:225], v[20:23]
	v_mfma_f32_16x16x32_bf16 v[12:15], v[112:115], v[218:221], v[12:15]
	v_mfma_f32_16x16x32_bf16 v[12:15], v[116:119], v[222:225], v[12:15]
	v_mfma_f32_16x16x32_bf16 v[52:55], v[144:147], v[160:163], v[52:55]
	v_mfma_f32_16x16x32_bf16 v[52:55], v[148:151], v[164:167], v[52:55]
	v_mfma_f32_16x16x32_bf16 v[48:51], v[152:155], v[160:163], v[48:51]
	v_mfma_f32_16x16x32_bf16 v[48:51], v[156:159], v[164:167], v[48:51]
	v_mfma_f32_16x16x32_bf16 v[32:35], v[144:147], v[196:199], v[32:35]
	v_mfma_f32_16x16x32_bf16 v[32:35], v[148:151], v[200:203], v[32:35]
	v_mfma_f32_16x16x32_bf16 v[24:27], v[152:155], v[196:199], v[24:27]
	v_mfma_f32_16x16x32_bf16 v[24:27], v[156:159], v[200:203], v[24:27]
	v_mfma_f32_16x16x32_bf16 v[16:19], v[144:147], v[210:213], v[16:19]
	v_mfma_f32_16x16x32_bf16 v[16:19], v[148:151], v[214:217], v[16:19]
	v_mfma_f32_16x16x32_bf16 v[8:11], v[152:155], v[210:213], v[8:11]
	v_mfma_f32_16x16x32_bf16 v[8:11], v[156:159], v[214:217], v[8:11]
	s_setprio 3
	s_barrier
	v_mfma_f32_16x16x32_bf16 v[4:7], v[144:147], v[218:221], v[4:7]
	v_mfma_f32_16x16x32_bf16 v[4:7], v[148:151], v[222:225], v[4:7]
	v_mfma_f32_16x16x32_bf16 v[0:3], v[152:155], v[218:221], v[0:3]
	v_mfma_f32_16x16x32_bf16 v[0:3], v[156:159], v[222:225], v[0:3]
	s_setprio 0
	s_add_u32 s57, s57, 0x100
	s_addc_u32 s59, s59, 0
	s_add_u32 s22, s22, 0x100
	s_addc_u32 s23, s23, 0
	s_cmp_ge_u32 s60, s46
	s_mov_b32 s24, s60
	s_cbranch_scc0 .LBB0_183

.LBB0_241:
	s_ashr_i32 s35, s34, 31
	s_lshl_b64 s[12:13], s[34:35], 19
	s_add_u32 s36, s40, s12
	s_addc_u32 s37, s41, s13
	s_and_b64 s[12:13], s[4:5], exec
	s_cselect_b32 s7, s37, s11
	s_cselect_b32 s35, s36, s10
	s_ashr_i32 s31, s30, 31
	s_lshl_b64 s[12:13], s[30:31], 19
	s_add_u32 s50, s42, s12
	s_addc_u32 s51, s43, s13
	s_and_b64 s[12:13], s[4:5], exec
	s_cselect_b32 s31, s51, s9
	s_cselect_b32 s89, s50, s8
	s_add_u32 vcc_lo, s8, 0x100
	s_addc_u32 vcc_hi, s9, 0
	s_add_u32 s8, s10, 0x40080
	v_mov_b32_e32 v0, 0
	s_addc_u32 s9, s11, 0
	s_mov_b32 s12, -2
	v_mov_b32_e32 v1, v0
	v_mov_b32_e32 v2, v0
	v_mov_b32_e32 v3, v0
	v_mov_b32_e32 v4, v0
	v_mov_b32_e32 v5, v0
	v_mov_b32_e32 v6, v0
	v_mov_b32_e32 v7, v0
	v_mov_b32_e32 v16, v0
	v_mov_b32_e32 v17, v0
	v_mov_b32_e32 v18, v0
	v_mov_b32_e32 v19, v0
	v_mov_b32_e32 v20, v0
	v_mov_b32_e32 v21, v0
	v_mov_b32_e32 v22, v0
	v_mov_b32_e32 v23, v0
	v_mov_b32_e32 v32, v0
	v_mov_b32_e32 v33, v0
	v_mov_b32_e32 v34, v0
	v_mov_b32_e32 v35, v0
	v_mov_b32_e32 v36, v0
	v_mov_b32_e32 v37, v0
	v_mov_b32_e32 v38, v0
	v_mov_b32_e32 v39, v0
	v_mov_b32_e32 v48, v0
	v_mov_b32_e32 v49, v0
	v_mov_b32_e32 v50, v0
	v_mov_b32_e32 v51, v0
	v_mov_b32_e32 v52, v0
	v_mov_b32_e32 v53, v0
	v_mov_b32_e32 v54, v0
	v_mov_b32_e32 v55, v0
	v_mov_b32_e32 v8, v0
	v_mov_b32_e32 v9, v0
	v_mov_b32_e32 v10, v0
	v_mov_b32_e32 v11, v0
	v_mov_b32_e32 v12, v0
	v_mov_b32_e32 v13, v0
	v_mov_b32_e32 v14, v0
	v_mov_b32_e32 v15, v0
	v_mov_b32_e32 v24, v0
	v_mov_b32_e32 v25, v0
	v_mov_b32_e32 v26, v0
	v_mov_b32_e32 v27, v0
	v_mov_b32_e32 v28, v0
	v_mov_b32_e32 v29, v0
	v_mov_b32_e32 v30, v0
	v_mov_b32_e32 v31, v0
	v_mov_b32_e32 v40, v0
	v_mov_b32_e32 v41, v0
	v_mov_b32_e32 v42, v0
	v_mov_b32_e32 v43, v0
	v_mov_b32_e32 v44, v0
	v_mov_b32_e32 v45, v0
	v_mov_b32_e32 v46, v0
	v_mov_b32_e32 v47, v0
	v_mov_b32_e32 v56, v0
	v_mov_b32_e32 v57, v0
	v_mov_b32_e32 v58, v0
	v_mov_b32_e32 v59, v0
	v_mov_b32_e32 v60, v0
	v_mov_b32_e32 v61, v0
	v_mov_b32_e32 v62, v0
	v_mov_b32_e32 v63, v0
	v_mov_b32_e32 v64, v0
	v_mov_b32_e32 v65, v0
	v_mov_b32_e32 v66, v0
	v_mov_b32_e32 v67, v0
	v_mov_b32_e32 v68, v0
	v_mov_b32_e32 v69, v0
	v_mov_b32_e32 v70, v0
	v_mov_b32_e32 v71, v0
	v_mov_b32_e32 v80, v0
	v_mov_b32_e32 v81, v0
	v_mov_b32_e32 v82, v0
	v_mov_b32_e32 v83, v0
	v_mov_b32_e32 v84, v0
	v_mov_b32_e32 v85, v0
	v_mov_b32_e32 v86, v0
	v_mov_b32_e32 v87, v0
	v_mov_b32_e32 v96, v0
	v_mov_b32_e32 v97, v0
	v_mov_b32_e32 v98, v0
	v_mov_b32_e32 v99, v0
	v_mov_b32_e32 v100, v0
	v_mov_b32_e32 v101, v0
	v_mov_b32_e32 v102, v0
	v_mov_b32_e32 v103, v0
	v_mov_b32_e32 v112, v0
	v_mov_b32_e32 v113, v0
	v_mov_b32_e32 v114, v0
	v_mov_b32_e32 v115, v0
	v_mov_b32_e32 v116, v0
	v_mov_b32_e32 v117, v0
	v_mov_b32_e32 v118, v0
	v_mov_b32_e32 v119, v0
	v_mov_b32_e32 v72, v0
	v_mov_b32_e32 v73, v0
	v_mov_b32_e32 v74, v0
	v_mov_b32_e32 v75, v0
	v_mov_b32_e32 v76, v0
	v_mov_b32_e32 v77, v0
	v_mov_b32_e32 v78, v0
	v_mov_b32_e32 v79, v0
	v_mov_b32_e32 v88, v0
	v_mov_b32_e32 v89, v0
	v_mov_b32_e32 v90, v0
	v_mov_b32_e32 v91, v0
	v_mov_b32_e32 v92, v0
	v_mov_b32_e32 v93, v0
	v_mov_b32_e32 v94, v0
	v_mov_b32_e32 v95, v0
	v_mov_b32_e32 v104, v0
	v_mov_b32_e32 v105, v0
	v_mov_b32_e32 v106, v0
	v_mov_b32_e32 v107, v0
	v_mov_b32_e32 v108, v0
	v_mov_b32_e32 v109, v0
	v_mov_b32_e32 v110, v0
	v_mov_b32_e32 v111, v0
	v_mov_b32_e32 v120, v0
	v_mov_b32_e32 v121, v0
	v_mov_b32_e32 v122, v0
	v_mov_b32_e32 v123, v0
	v_mov_b32_e32 v124, v0
	v_mov_b32_e32 v125, v0
	v_mov_b32_e32 v126, v0
	v_mov_b32_e32 v127, v0
	v_readlane_b32 s2, v246, 42
	s_cmp_eq_u32 s2, 0
	s_cbranch_scc1 .LBB0_242
	s_add_u32 s2, s8, 0xfffc0080
	s_addc_u32 s3, s9, -1
	s_add_i32 s13, 0, 0x10000
	s_cmp_eq_u32 s12, 12
	s_cselect_b32 s53, s7, s3
	s_cselect_b32 s52, s35, s2
	v_add_u32_e32 v156, s13, v164
	s_cselect_b32 s11, s31, vcc_hi
	s_cselect_b32 s10, s89, vcc_lo
	s_add_i32 s77, 0, 0x14000
	ds_read_b128 v[144:147], v156
	ds_read_b128 v[148:151], v156 offset:1024
	ds_read_b128 v[152:155], v156 offset:2048
	ds_read_b128 v[166:169], v156 offset:3072
	v_add_u32_e32 v156, s77, v164
	ds_read_b128 v[184:187], v156
	ds_read_b128 v[188:191], v156 offset:1024
	ds_read_b128 v[192:195], v156 offset:2048
	ds_read_b128 v[196:199], v156 offset:3072
	v_lshl_add_u64 v[156:157], s[8:9], 0, v[142:143]
	s_add_i32 m0, s19, 0xc000
	ds_read_b128 v[200:203], v165
	ds_read_b128 v[210:213], v165 offset:1024
	ds_read_b128 v[214:217], v165 offset:2048
	ds_read_b128 v[218:221], v165 offset:3072
	ds_read_b128 v[222:225], v165 offset:4096
	ds_read_b128 v[226:229], v165 offset:5120
	ds_read_b128 v[230:233], v165 offset:6144
	ds_read_b128 v[234:237], v165 offset:7168
	global_load_lds_dwordx4 v[156:157], off
	v_lshl_add_u64 v[156:157], s[8:9], 0, v[140:141]
	s_add_i32 m0, s19, 0xe000
	s_nop 0
	global_load_lds_dwordx4 v[156:157], off
	s_waitcnt vmcnt(24)
	s_waitcnt lgkmcnt(0)
	s_setprio 1
	s_barrier
	v_mfma_f32_16x16x32_bf16 v[124:127], v[144:147], v[200:203], v[124:127]
	v_mfma_f32_16x16x32_bf16 v[124:127], v[148:151], v[210:213], v[124:127]
	v_mfma_f32_16x16x32_bf16 v[120:123], v[152:155], v[200:203], v[120:123]
	v_mfma_f32_16x16x32_bf16 v[120:123], v[166:169], v[210:213], v[120:123]
	v_mfma_f32_16x16x32_bf16 v[108:111], v[144:147], v[214:217], v[108:111]
	v_mfma_f32_16x16x32_bf16 v[108:111], v[148:151], v[218:221], v[108:111]
	v_mfma_f32_16x16x32_bf16 v[104:107], v[152:155], v[214:217], v[104:107]
	v_mfma_f32_16x16x32_bf16 v[104:107], v[166:169], v[218:221], v[104:107]
	v_mfma_f32_16x16x32_bf16 v[92:95], v[144:147], v[222:225], v[92:95]
	v_mfma_f32_16x16x32_bf16 v[92:95], v[148:151], v[226:229], v[92:95]
	v_mfma_f32_16x16x32_bf16 v[88:91], v[152:155], v[222:225], v[88:91]
	v_mfma_f32_16x16x32_bf16 v[88:91], v[166:169], v[226:229], v[88:91]
	v_mfma_f32_16x16x32_bf16 v[76:79], v[144:147], v[230:233], v[76:79]
	v_mfma_f32_16x16x32_bf16 v[76:79], v[148:151], v[234:237], v[76:79]
	v_mfma_f32_16x16x32_bf16 v[72:75], v[152:155], v[230:233], v[72:75]
	v_mfma_f32_16x16x32_bf16 v[72:75], v[166:169], v[234:237], v[72:75]
	v_mfma_f32_16x16x32_bf16 v[116:119], v[184:187], v[200:203], v[116:119]
	v_mfma_f32_16x16x32_bf16 v[116:119], v[188:191], v[210:213], v[116:119]
	v_mfma_f32_16x16x32_bf16 v[112:115], v[192:195], v[200:203], v[112:115]
	v_mfma_f32_16x16x32_bf16 v[112:115], v[196:199], v[210:213], v[112:115]
	v_mfma_f32_16x16x32_bf16 v[100:103], v[184:187], v[214:217], v[100:103]
	v_mfma_f32_16x16x32_bf16 v[100:103], v[188:191], v[218:221], v[100:103]
	v_mfma_f32_16x16x32_bf16 v[96:99], v[192:195], v[214:217], v[96:99]
	v_mfma_f32_16x16x32_bf16 v[96:99], v[196:199], v[218:221], v[96:99]
	v_mfma_f32_16x16x32_bf16 v[84:87], v[184:187], v[222:225], v[84:87]
	v_mfma_f32_16x16x32_bf16 v[84:87], v[188:191], v[226:229], v[84:87]
	v_mfma_f32_16x16x32_bf16 v[80:83], v[192:195], v[222:225], v[80:83]
	v_mfma_f32_16x16x32_bf16 v[80:83], v[196:199], v[226:229], v[80:83]
	s_setprio 3
	s_barrier
	v_mfma_f32_16x16x32_bf16 v[68:71], v[184:187], v[230:233], v[68:71]
	v_mfma_f32_16x16x32_bf16 v[68:71], v[188:191], v[234:237], v[68:71]
	v_mfma_f32_16x16x32_bf16 v[64:67], v[192:195], v[230:233], v[64:67]
	v_mfma_f32_16x16x32_bf16 v[64:67], v[196:199], v[234:237], v[64:67]
	s_setprio 0
	s_add_i32 s2, s13, s56
	v_lshl_add_u64 v[156:157], s[10:11], 0, v[174:175]
	s_mov_b32 m0, s2
	ds_read_b128 v[200:203], v165 offset:16384
	ds_read_b128 v[210:213], v165 offset:17408
	ds_read_b128 v[214:217], v165 offset:18432
	ds_read_b128 v[218:221], v165 offset:19456
	ds_read_b128 v[222:225], v165 offset:20480
	ds_read_b128 v[226:229], v165 offset:21504
	ds_read_b128 v[230:233], v165 offset:22528
	ds_read_b128 v[234:237], v165 offset:23552
	global_load_lds_dwordx4 v[156:157], off
	s_add_i32 m0, s2, 0x2000
	s_add_u32 s2, s10, 0x40000
	v_lshl_add_u64 v[170:171], s[10:11], 0, v[132:133]
	s_addc_u32 s3, s11, 0
	s_add_i32 s13, s77, s56
	global_load_lds_dwordx4 v[170:171], off
	v_lshl_add_u64 v[238:239], s[2:3], 0, v[174:175]
	s_mov_b32 m0, s13
	v_lshl_add_u64 v[240:241], s[52:53], 0, v[130:131]
	global_load_lds_dwordx4 v[238:239], off
	v_lshl_add_u64 v[238:239], s[2:3], 0, v[132:133]
	s_add_i32 m0, s13, 0x2000
	s_nop 0
	global_load_lds_dwordx4 v[238:239], off
	v_lshl_add_u64 v[238:239], s[52:53], 0, v[128:129]
	s_mov_b32 m0, s19
	s_nop 0
	global_load_lds_dwordx4 v[238:239], off
	s_mov_b32 m0, s57
	s_nop 0
	global_load_lds_dwordx4 v[240:241], off
	s_waitcnt vmcnt(24)
	s_waitcnt lgkmcnt(0)
	s_setprio 1
	s_barrier
	v_mfma_f32_16x16x32_bf16 v[60:63], v[144:147], v[200:203], v[60:63]
	v_mfma_f32_16x16x32_bf16 v[60:63], v[148:151], v[210:213], v[60:63]
	v_mfma_f32_16x16x32_bf16 v[56:59], v[152:155], v[200:203], v[56:59]
	v_mfma_f32_16x16x32_bf16 v[56:59], v[166:169], v[210:213], v[56:59]
	v_mfma_f32_16x16x32_bf16 v[44:47], v[144:147], v[214:217], v[44:47]
	v_mfma_f32_16x16x32_bf16 v[44:47], v[148:151], v[218:221], v[44:47]
	v_mfma_f32_16x16x32_bf16 v[40:43], v[152:155], v[214:217], v[40:43]
	v_mfma_f32_16x16x32_bf16 v[40:43], v[166:169], v[218:221], v[40:43]
	v_mfma_f32_16x16x32_bf16 v[28:31], v[144:147], v[222:225], v[28:31]
	v_mfma_f32_16x16x32_bf16 v[28:31], v[148:151], v[226:229], v[28:31]
	v_mfma_f32_16x16x32_bf16 v[24:27], v[152:155], v[222:225], v[24:27]
	v_mfma_f32_16x16x32_bf16 v[24:27], v[166:169], v[226:229], v[24:27]
	v_mfma_f32_16x16x32_bf16 v[12:15], v[144:147], v[230:233], v[12:15]
	v_mfma_f32_16x16x32_bf16 v[12:15], v[148:151], v[234:237], v[12:15]
	v_mfma_f32_16x16x32_bf16 v[8:11], v[152:155], v[230:233], v[8:11]
	v_mfma_f32_16x16x32_bf16 v[8:11], v[166:169], v[234:237], v[8:11]
	v_mfma_f32_16x16x32_bf16 v[52:55], v[184:187], v[200:203], v[52:55]
	v_mfma_f32_16x16x32_bf16 v[52:55], v[188:191], v[210:213], v[52:55]
	v_mfma_f32_16x16x32_bf16 v[48:51], v[192:195], v[200:203], v[48:51]
	v_mfma_f32_16x16x32_bf16 v[48:51], v[196:199], v[210:213], v[48:51]
	v_mfma_f32_16x16x32_bf16 v[36:39], v[184:187], v[214:217], v[36:39]
	v_mfma_f32_16x16x32_bf16 v[36:39], v[188:191], v[218:221], v[36:39]
	v_mfma_f32_16x16x32_bf16 v[32:35], v[192:195], v[214:217], v[32:35]
	v_mfma_f32_16x16x32_bf16 v[32:35], v[196:199], v[218:221], v[32:35]
	v_mfma_f32_16x16x32_bf16 v[20:23], v[184:187], v[222:225], v[20:23]
	v_mfma_f32_16x16x32_bf16 v[20:23], v[188:191], v[226:229], v[20:23]
	v_mfma_f32_16x16x32_bf16 v[16:19], v[192:195], v[222:225], v[16:19]
	v_mfma_f32_16x16x32_bf16 v[16:19], v[196:199], v[226:229], v[16:19]
	s_setprio 3
	s_barrier
	v_mfma_f32_16x16x32_bf16 v[4:7], v[184:187], v[230:233], v[4:7]
	v_mfma_f32_16x16x32_bf16 v[4:7], v[188:191], v[234:237], v[4:7]
	v_mfma_f32_16x16x32_bf16 v[0:3], v[192:195], v[230:233], v[0:3]
	v_mfma_f32_16x16x32_bf16 v[0:3], v[196:199], v[234:237], v[0:3]
	s_setprio 0
	s_add_i32 s13, 0, 0x18000
	s_add_i32 s77, 0, 0x1c000
	v_add_u32_e32 v166, s13, v164
	v_add_u32_e32 v183, s77, v164
	ds_read_b128 v[144:147], v166
	ds_read_b128 v[148:151], v166 offset:1024
	ds_read_b128 v[152:155], v166 offset:2048
	ds_read_b128 v[166:169], v166 offset:3072
	ds_read_b128 v[184:187], v183
	ds_read_b128 v[188:191], v183 offset:1024
	ds_read_b128 v[192:195], v183 offset:2048
	ds_read_b128 v[196:199], v183 offset:3072
	s_add_u32 s2, s52, 0x40000
	s_addc_u32 s3, s53, 0
	s_mov_b32 m0, s60
	v_lshl_add_u64 v[242:243], s[2:3], 0, v[128:129]
	ds_read_b128 v[200:203], v165 offset:32768
	ds_read_b128 v[210:213], v165 offset:33792
	ds_read_b128 v[214:217], v165 offset:34816
	ds_read_b128 v[218:221], v165 offset:35840
	ds_read_b128 v[222:225], v165 offset:36864
	ds_read_b128 v[226:229], v165 offset:37888
	ds_read_b128 v[230:233], v165 offset:38912
	ds_read_b128 v[234:237], v165 offset:39936
	global_load_lds_dwordx4 v[242:243], off
	v_lshl_add_u64 v[242:243], s[2:3], 0, v[130:131]
	s_mov_b32 m0, s61
	s_nop 0
	global_load_lds_dwordx4 v[242:243], off
	s_waitcnt vmcnt(8)
	s_waitcnt lgkmcnt(0)
	s_setprio 1
	s_barrier
	v_mfma_f32_16x16x32_bf16 v[124:127], v[144:147], v[200:203], v[124:127]
	v_mfma_f32_16x16x32_bf16 v[124:127], v[148:151], v[210:213], v[124:127]
	v_mfma_f32_16x16x32_bf16 v[120:123], v[152:155], v[200:203], v[120:123]
	v_mfma_f32_16x16x32_bf16 v[120:123], v[166:169], v[210:213], v[120:123]
	v_mfma_f32_16x16x32_bf16 v[108:111], v[144:147], v[214:217], v[108:111]
	v_mfma_f32_16x16x32_bf16 v[108:111], v[148:151], v[218:221], v[108:111]
	v_mfma_f32_16x16x32_bf16 v[104:107], v[152:155], v[214:217], v[104:107]
	v_mfma_f32_16x16x32_bf16 v[104:107], v[166:169], v[218:221], v[104:107]
	v_mfma_f32_16x16x32_bf16 v[92:95], v[144:147], v[222:225], v[92:95]
	v_mfma_f32_16x16x32_bf16 v[92:95], v[148:151], v[226:229], v[92:95]
	v_mfma_f32_16x16x32_bf16 v[88:91], v[152:155], v[222:225], v[88:91]
	v_mfma_f32_16x16x32_bf16 v[88:91], v[166:169], v[226:229], v[88:91]
	v_mfma_f32_16x16x32_bf16 v[76:79], v[144:147], v[230:233], v[76:79]
	v_mfma_f32_16x16x32_bf16 v[76:79], v[148:151], v[234:237], v[76:79]
	v_mfma_f32_16x16x32_bf16 v[72:75], v[152:155], v[230:233], v[72:75]
	v_mfma_f32_16x16x32_bf16 v[72:75], v[166:169], v[234:237], v[72:75]
	v_mfma_f32_16x16x32_bf16 v[116:119], v[184:187], v[200:203], v[116:119]
	v_mfma_f32_16x16x32_bf16 v[116:119], v[188:191], v[210:213], v[116:119]
	v_mfma_f32_16x16x32_bf16 v[112:115], v[192:195], v[200:203], v[112:115]
	v_mfma_f32_16x16x32_bf16 v[112:115], v[196:199], v[210:213], v[112:115]
	v_mfma_f32_16x16x32_bf16 v[100:103], v[184:187], v[214:217], v[100:103]
	v_mfma_f32_16x16x32_bf16 v[100:103], v[188:191], v[218:221], v[100:103]
	v_mfma_f32_16x16x32_bf16 v[96:99], v[192:195], v[214:217], v[96:99]
	v_mfma_f32_16x16x32_bf16 v[96:99], v[196:199], v[218:221], v[96:99]
	v_mfma_f32_16x16x32_bf16 v[84:87], v[184:187], v[222:225], v[84:87]
	v_mfma_f32_16x16x32_bf16 v[84:87], v[188:191], v[226:229], v[84:87]
	v_mfma_f32_16x16x32_bf16 v[80:83], v[192:195], v[222:225], v[80:83]
	v_mfma_f32_16x16x32_bf16 v[80:83], v[196:199], v[226:229], v[80:83]
	s_setprio 3
	s_barrier
	v_mfma_f32_16x16x32_bf16 v[68:71], v[184:187], v[230:233], v[68:71]
	v_mfma_f32_16x16x32_bf16 v[68:71], v[188:191], v[234:237], v[68:71]
	v_mfma_f32_16x16x32_bf16 v[64:67], v[192:195], v[230:233], v[64:67]
	v_mfma_f32_16x16x32_bf16 v[64:67], v[196:199], v[234:237], v[64:67]
	s_setprio 0
	s_add_i32 s2, s13, s56
	v_lshl_add_u64 v[156:157], v[156:157], 0, s[82:83]
	s_mov_b32 m0, s2
	ds_read_b128 v[200:203], v165 offset:49152
	ds_read_b128 v[210:213], v165 offset:50176
	ds_read_b128 v[214:217], v165 offset:51200
	ds_read_b128 v[218:221], v165 offset:52224
	ds_read_b128 v[222:225], v165 offset:53248
	ds_read_b128 v[226:229], v165 offset:54272
	ds_read_b128 v[230:233], v165 offset:55296
	ds_read_b128 v[234:237], v165 offset:56320
	global_load_lds_dwordx4 v[156:157], off
	s_add_i32 m0, s2, 0x2000
	s_add_u32 s2, s10, 0x40080
	v_lshl_add_u64 v[156:157], v[170:171], 0, s[82:83]
	s_addc_u32 s3, s11, 0
	s_add_i32 s10, s77, s56
	global_load_lds_dwordx4 v[156:157], off
	v_lshl_add_u64 v[156:157], s[2:3], 0, v[174:175]
	s_mov_b32 m0, s10
	s_nop 0
	global_load_lds_dwordx4 v[156:157], off
	v_lshl_add_u64 v[156:157], s[2:3], 0, v[132:133]
	s_add_i32 m0, s10, 0x2000
	s_nop 0
	global_load_lds_dwordx4 v[156:157], off
	v_lshl_add_u64 v[156:157], v[238:239], 0, s[82:83]
	s_mov_b32 m0, s39
	s_nop 0
	global_load_lds_dwordx4 v[156:157], off
	v_lshl_add_u64 v[156:157], v[240:241], 0, s[82:83]
	s_mov_b32 m0, s46
	s_nop 0
	global_load_lds_dwordx4 v[156:157], off
	s_waitcnt vmcnt(8)
	s_waitcnt lgkmcnt(0)
	s_setprio 1
	s_barrier
	v_mfma_f32_16x16x32_bf16 v[60:63], v[144:147], v[200:203], v[60:63]
	v_mfma_f32_16x16x32_bf16 v[60:63], v[148:151], v[210:213], v[60:63]
	v_mfma_f32_16x16x32_bf16 v[56:59], v[152:155], v[200:203], v[56:59]
	v_mfma_f32_16x16x32_bf16 v[56:59], v[166:169], v[210:213], v[56:59]
	v_mfma_f32_16x16x32_bf16 v[44:47], v[144:147], v[214:217], v[44:47]
	v_mfma_f32_16x16x32_bf16 v[44:47], v[148:151], v[218:221], v[44:47]
	v_mfma_f32_16x16x32_bf16 v[40:43], v[152:155], v[214:217], v[40:43]
	v_mfma_f32_16x16x32_bf16 v[40:43], v[166:169], v[218:221], v[40:43]
	v_mfma_f32_16x16x32_bf16 v[28:31], v[144:147], v[222:225], v[28:31]
	v_mfma_f32_16x16x32_bf16 v[28:31], v[148:151], v[226:229], v[28:31]
	v_mfma_f32_16x16x32_bf16 v[24:27], v[152:155], v[222:225], v[24:27]
	v_mfma_f32_16x16x32_bf16 v[24:27], v[166:169], v[226:229], v[24:27]
	v_mfma_f32_16x16x32_bf16 v[12:15], v[144:147], v[230:233], v[12:15]
	v_mfma_f32_16x16x32_bf16 v[12:15], v[148:151], v[234:237], v[12:15]
	v_mfma_f32_16x16x32_bf16 v[8:11], v[152:155], v[230:233], v[8:11]
	v_mfma_f32_16x16x32_bf16 v[8:11], v[166:169], v[234:237], v[8:11]
	v_mfma_f32_16x16x32_bf16 v[52:55], v[184:187], v[200:203], v[52:55]
	v_mfma_f32_16x16x32_bf16 v[52:55], v[188:191], v[210:213], v[52:55]
	v_mfma_f32_16x16x32_bf16 v[48:51], v[192:195], v[200:203], v[48:51]
	v_mfma_f32_16x16x32_bf16 v[48:51], v[196:199], v[210:213], v[48:51]
	v_mfma_f32_16x16x32_bf16 v[36:39], v[184:187], v[214:217], v[36:39]
	v_mfma_f32_16x16x32_bf16 v[36:39], v[188:191], v[218:221], v[36:39]
	v_mfma_f32_16x16x32_bf16 v[32:35], v[192:195], v[214:217], v[32:35]
	v_mfma_f32_16x16x32_bf16 v[32:35], v[196:199], v[218:221], v[32:35]
	v_mfma_f32_16x16x32_bf16 v[20:23], v[184:187], v[222:225], v[20:23]
	v_mfma_f32_16x16x32_bf16 v[20:23], v[188:191], v[226:229], v[20:23]
	v_mfma_f32_16x16x32_bf16 v[16:19], v[192:195], v[222:225], v[16:19]
	v_mfma_f32_16x16x32_bf16 v[16:19], v[196:199], v[226:229], v[16:19]
	s_setprio 3
	s_barrier
	v_mfma_f32_16x16x32_bf16 v[4:7], v[184:187], v[230:233], v[4:7]
	v_mfma_f32_16x16x32_bf16 v[4:7], v[188:191], v[234:237], v[4:7]
	v_mfma_f32_16x16x32_bf16 v[0:3], v[192:195], v[230:233], v[0:3]
	v_mfma_f32_16x16x32_bf16 v[0:3], v[196:199], v[234:237], v[0:3]
	s_setprio 0
	s_add_i32 s12, s12, 2
	s_add_u32 vcc_lo, vcc_lo, 0x100
	s_addc_u32 vcc_hi, vcc_hi, 0
	s_add_u32 s8, s8, 0x100
	s_addc_u32 s9, s9, 0
	s_cmp_gt_u32 s12, 13
	s_cbranch_scc1 .Lexit_242
.LBB0_242:
	s_add_u32 s2, s8, 0xfffc0080
	s_addc_u32 s3, s9, -1
	s_add_i32 s13, 0, 0x10000
	s_cmp_eq_u32 s12, 12
	s_cselect_b32 s53, s7, s3
	s_cselect_b32 s52, s35, s2
	v_add_u32_e32 v156, s13, v164
	s_cselect_b32 s11, s31, vcc_hi
	s_cselect_b32 s10, s89, vcc_lo
	s_add_i32 s77, 0, 0x14000
	ds_read_b128 v[144:147], v156
	ds_read_b128 v[148:151], v156 offset:1024
	ds_read_b128 v[152:155], v156 offset:2048
	ds_read_b128 v[166:169], v156 offset:3072
	v_add_u32_e32 v156, s77, v164
	ds_read_b128 v[184:187], v156
	ds_read_b128 v[188:191], v156 offset:1024
	ds_read_b128 v[192:195], v156 offset:2048
	ds_read_b128 v[196:199], v156 offset:3072
	v_lshl_add_u64 v[156:157], s[8:9], 0, v[142:143]
	s_add_i32 m0, s19, 0xc000
	ds_read_b128 v[200:203], v165
	ds_read_b128 v[210:213], v165 offset:1024
	ds_read_b128 v[214:217], v165 offset:2048
	ds_read_b128 v[218:221], v165 offset:3072
	ds_read_b128 v[222:225], v165 offset:4096
	ds_read_b128 v[226:229], v165 offset:5120
	ds_read_b128 v[230:233], v165 offset:6144
	ds_read_b128 v[234:237], v165 offset:7168
	global_load_lds_dwordx4 v[156:157], off
	v_lshl_add_u64 v[156:157], s[8:9], 0, v[140:141]
	s_add_i32 m0, s19, 0xe000
	s_nop 0
	global_load_lds_dwordx4 v[156:157], off
	s_waitcnt vmcnt(8)
	s_waitcnt lgkmcnt(0)
	s_setprio 1
	s_barrier
	v_mfma_f32_16x16x32_bf16 v[124:127], v[144:147], v[200:203], v[124:127]
	v_mfma_f32_16x16x32_bf16 v[124:127], v[148:151], v[210:213], v[124:127]
	v_mfma_f32_16x16x32_bf16 v[120:123], v[152:155], v[200:203], v[120:123]
	v_mfma_f32_16x16x32_bf16 v[120:123], v[166:169], v[210:213], v[120:123]
	v_mfma_f32_16x16x32_bf16 v[108:111], v[144:147], v[214:217], v[108:111]
	v_mfma_f32_16x16x32_bf16 v[108:111], v[148:151], v[218:221], v[108:111]
	v_mfma_f32_16x16x32_bf16 v[104:107], v[152:155], v[214:217], v[104:107]
	v_mfma_f32_16x16x32_bf16 v[104:107], v[166:169], v[218:221], v[104:107]
	v_mfma_f32_16x16x32_bf16 v[92:95], v[144:147], v[222:225], v[92:95]
	v_mfma_f32_16x16x32_bf16 v[92:95], v[148:151], v[226:229], v[92:95]
	v_mfma_f32_16x16x32_bf16 v[88:91], v[152:155], v[222:225], v[88:91]
	v_mfma_f32_16x16x32_bf16 v[88:91], v[166:169], v[226:229], v[88:91]
	v_mfma_f32_16x16x32_bf16 v[76:79], v[144:147], v[230:233], v[76:79]
	v_mfma_f32_16x16x32_bf16 v[76:79], v[148:151], v[234:237], v[76:79]
	v_mfma_f32_16x16x32_bf16 v[72:75], v[152:155], v[230:233], v[72:75]
	v_mfma_f32_16x16x32_bf16 v[72:75], v[166:169], v[234:237], v[72:75]
	v_mfma_f32_16x16x32_bf16 v[116:119], v[184:187], v[200:203], v[116:119]
	v_mfma_f32_16x16x32_bf16 v[116:119], v[188:191], v[210:213], v[116:119]
	v_mfma_f32_16x16x32_bf16 v[112:115], v[192:195], v[200:203], v[112:115]
	v_mfma_f32_16x16x32_bf16 v[112:115], v[196:199], v[210:213], v[112:115]
	v_mfma_f32_16x16x32_bf16 v[100:103], v[184:187], v[214:217], v[100:103]
	v_mfma_f32_16x16x32_bf16 v[100:103], v[188:191], v[218:221], v[100:103]
	v_mfma_f32_16x16x32_bf16 v[96:99], v[192:195], v[214:217], v[96:99]
	v_mfma_f32_16x16x32_bf16 v[96:99], v[196:199], v[218:221], v[96:99]
	v_mfma_f32_16x16x32_bf16 v[84:87], v[184:187], v[222:225], v[84:87]
	v_mfma_f32_16x16x32_bf16 v[84:87], v[188:191], v[226:229], v[84:87]
	v_mfma_f32_16x16x32_bf16 v[80:83], v[192:195], v[222:225], v[80:83]
	v_mfma_f32_16x16x32_bf16 v[80:83], v[196:199], v[226:229], v[80:83]
	s_setprio 3
	s_barrier
	v_mfma_f32_16x16x32_bf16 v[68:71], v[184:187], v[230:233], v[68:71]
	v_mfma_f32_16x16x32_bf16 v[68:71], v[188:191], v[234:237], v[68:71]
	v_mfma_f32_16x16x32_bf16 v[64:67], v[192:195], v[230:233], v[64:67]
	v_mfma_f32_16x16x32_bf16 v[64:67], v[196:199], v[234:237], v[64:67]
	s_setprio 0
	s_add_i32 s2, s13, s56
	v_lshl_add_u64 v[156:157], s[10:11], 0, v[174:175]
	s_mov_b32 m0, s2
	ds_read_b128 v[200:203], v165 offset:16384
	ds_read_b128 v[210:213], v165 offset:17408
	ds_read_b128 v[214:217], v165 offset:18432
	ds_read_b128 v[218:221], v165 offset:19456
	ds_read_b128 v[222:225], v165 offset:20480
	ds_read_b128 v[226:229], v165 offset:21504
	ds_read_b128 v[230:233], v165 offset:22528
	ds_read_b128 v[234:237], v165 offset:23552
	global_load_lds_dwordx4 v[156:157], off
	s_add_i32 m0, s2, 0x2000
	s_add_u32 s2, s10, 0x40000
	v_lshl_add_u64 v[170:171], s[10:11], 0, v[132:133]
	s_addc_u32 s3, s11, 0
	s_add_i32 s13, s77, s56
	global_load_lds_dwordx4 v[170:171], off
	v_lshl_add_u64 v[238:239], s[2:3], 0, v[174:175]
	s_mov_b32 m0, s13
	v_lshl_add_u64 v[240:241], s[52:53], 0, v[130:131]
	global_load_lds_dwordx4 v[238:239], off
	v_lshl_add_u64 v[238:239], s[2:3], 0, v[132:133]
	s_add_i32 m0, s13, 0x2000
	s_nop 0
	global_load_lds_dwordx4 v[238:239], off
	v_lshl_add_u64 v[238:239], s[52:53], 0, v[128:129]
	s_mov_b32 m0, s19
	s_nop 0
	global_load_lds_dwordx4 v[238:239], off
	s_mov_b32 m0, s57
	s_nop 0
	global_load_lds_dwordx4 v[240:241], off
	s_waitcnt vmcnt(8)
	s_waitcnt lgkmcnt(0)
	s_setprio 1
	s_barrier
	v_mfma_f32_16x16x32_bf16 v[60:63], v[144:147], v[200:203], v[60:63]
	v_mfma_f32_16x16x32_bf16 v[60:63], v[148:151], v[210:213], v[60:63]
	v_mfma_f32_16x16x32_bf16 v[56:59], v[152:155], v[200:203], v[56:59]
	v_mfma_f32_16x16x32_bf16 v[56:59], v[166:169], v[210:213], v[56:59]
	v_mfma_f32_16x16x32_bf16 v[44:47], v[144:147], v[214:217], v[44:47]
	v_mfma_f32_16x16x32_bf16 v[44:47], v[148:151], v[218:221], v[44:47]
	v_mfma_f32_16x16x32_bf16 v[40:43], v[152:155], v[214:217], v[40:43]
	v_mfma_f32_16x16x32_bf16 v[40:43], v[166:169], v[218:221], v[40:43]
	v_mfma_f32_16x16x32_bf16 v[28:31], v[144:147], v[222:225], v[28:31]
	v_mfma_f32_16x16x32_bf16 v[28:31], v[148:151], v[226:229], v[28:31]
	v_mfma_f32_16x16x32_bf16 v[24:27], v[152:155], v[222:225], v[24:27]
	v_mfma_f32_16x16x32_bf16 v[24:27], v[166:169], v[226:229], v[24:27]
	v_mfma_f32_16x16x32_bf16 v[12:15], v[144:147], v[230:233], v[12:15]
	v_mfma_f32_16x16x32_bf16 v[12:15], v[148:151], v[234:237], v[12:15]
	v_mfma_f32_16x16x32_bf16 v[8:11], v[152:155], v[230:233], v[8:11]
	v_mfma_f32_16x16x32_bf16 v[8:11], v[166:169], v[234:237], v[8:11]
	v_mfma_f32_16x16x32_bf16 v[52:55], v[184:187], v[200:203], v[52:55]
	v_mfma_f32_16x16x32_bf16 v[52:55], v[188:191], v[210:213], v[52:55]
	v_mfma_f32_16x16x32_bf16 v[48:51], v[192:195], v[200:203], v[48:51]
	v_mfma_f32_16x16x32_bf16 v[48:51], v[196:199], v[210:213], v[48:51]
	v_mfma_f32_16x16x32_bf16 v[36:39], v[184:187], v[214:217], v[36:39]
	v_mfma_f32_16x16x32_bf16 v[36:39], v[188:191], v[218:221], v[36:39]
	v_mfma_f32_16x16x32_bf16 v[32:35], v[192:195], v[214:217], v[32:35]
	v_mfma_f32_16x16x32_bf16 v[32:35], v[196:199], v[218:221], v[32:35]
	v_mfma_f32_16x16x32_bf16 v[20:23], v[184:187], v[222:225], v[20:23]
	v_mfma_f32_16x16x32_bf16 v[20:23], v[188:191], v[226:229], v[20:23]
	v_mfma_f32_16x16x32_bf16 v[16:19], v[192:195], v[222:225], v[16:19]
	v_mfma_f32_16x16x32_bf16 v[16:19], v[196:199], v[226:229], v[16:19]
	s_setprio 3
	s_barrier
	v_mfma_f32_16x16x32_bf16 v[4:7], v[184:187], v[230:233], v[4:7]
	v_mfma_f32_16x16x32_bf16 v[4:7], v[188:191], v[234:237], v[4:7]
	v_mfma_f32_16x16x32_bf16 v[0:3], v[192:195], v[230:233], v[0:3]
	v_mfma_f32_16x16x32_bf16 v[0:3], v[196:199], v[234:237], v[0:3]
	s_setprio 0
	s_add_i32 s13, 0, 0x18000
	s_add_i32 s77, 0, 0x1c000
	v_add_u32_e32 v166, s13, v164
	v_add_u32_e32 v183, s77, v164
	ds_read_b128 v[144:147], v166
	ds_read_b128 v[148:151], v166 offset:1024
	ds_read_b128 v[152:155], v166 offset:2048
	ds_read_b128 v[166:169], v166 offset:3072
	ds_read_b128 v[184:187], v183
	ds_read_b128 v[188:191], v183 offset:1024
	ds_read_b128 v[192:195], v183 offset:2048
	ds_read_b128 v[196:199], v183 offset:3072
	s_add_u32 s2, s52, 0x40000
	s_addc_u32 s3, s53, 0
	s_mov_b32 m0, s60
	v_lshl_add_u64 v[242:243], s[2:3], 0, v[128:129]
	ds_read_b128 v[200:203], v165 offset:32768
	ds_read_b128 v[210:213], v165 offset:33792
	ds_read_b128 v[214:217], v165 offset:34816
	ds_read_b128 v[218:221], v165 offset:35840
	ds_read_b128 v[222:225], v165 offset:36864
	ds_read_b128 v[226:229], v165 offset:37888
	ds_read_b128 v[230:233], v165 offset:38912
	ds_read_b128 v[234:237], v165 offset:39936
	global_load_lds_dwordx4 v[242:243], off
	v_lshl_add_u64 v[242:243], s[2:3], 0, v[130:131]
	s_mov_b32 m0, s61
	s_nop 0
	global_load_lds_dwordx4 v[242:243], off
	s_waitcnt vmcnt(8)
	s_waitcnt lgkmcnt(0)
	s_setprio 1
	s_barrier
	v_mfma_f32_16x16x32_bf16 v[124:127], v[144:147], v[200:203], v[124:127]
	v_mfma_f32_16x16x32_bf16 v[124:127], v[148:151], v[210:213], v[124:127]
	v_mfma_f32_16x16x32_bf16 v[120:123], v[152:155], v[200:203], v[120:123]
	v_mfma_f32_16x16x32_bf16 v[120:123], v[166:169], v[210:213], v[120:123]
	v_mfma_f32_16x16x32_bf16 v[108:111], v[144:147], v[214:217], v[108:111]
	v_mfma_f32_16x16x32_bf16 v[108:111], v[148:151], v[218:221], v[108:111]
	v_mfma_f32_16x16x32_bf16 v[104:107], v[152:155], v[214:217], v[104:107]
	v_mfma_f32_16x16x32_bf16 v[104:107], v[166:169], v[218:221], v[104:107]
	v_mfma_f32_16x16x32_bf16 v[92:95], v[144:147], v[222:225], v[92:95]
	v_mfma_f32_16x16x32_bf16 v[92:95], v[148:151], v[226:229], v[92:95]
	v_mfma_f32_16x16x32_bf16 v[88:91], v[152:155], v[222:225], v[88:91]
	v_mfma_f32_16x16x32_bf16 v[88:91], v[166:169], v[226:229], v[88:91]
	v_mfma_f32_16x16x32_bf16 v[76:79], v[144:147], v[230:233], v[76:79]
	v_mfma_f32_16x16x32_bf16 v[76:79], v[148:151], v[234:237], v[76:79]
	v_mfma_f32_16x16x32_bf16 v[72:75], v[152:155], v[230:233], v[72:75]
	v_mfma_f32_16x16x32_bf16 v[72:75], v[166:169], v[234:237], v[72:75]
	v_mfma_f32_16x16x32_bf16 v[116:119], v[184:187], v[200:203], v[116:119]
	v_mfma_f32_16x16x32_bf16 v[116:119], v[188:191], v[210:213], v[116:119]
	v_mfma_f32_16x16x32_bf16 v[112:115], v[192:195], v[200:203], v[112:115]
	v_mfma_f32_16x16x32_bf16 v[112:115], v[196:199], v[210:213], v[112:115]
	v_mfma_f32_16x16x32_bf16 v[100:103], v[184:187], v[214:217], v[100:103]
	v_mfma_f32_16x16x32_bf16 v[100:103], v[188:191], v[218:221], v[100:103]
	v_mfma_f32_16x16x32_bf16 v[96:99], v[192:195], v[214:217], v[96:99]
	v_mfma_f32_16x16x32_bf16 v[96:99], v[196:199], v[218:221], v[96:99]
	v_mfma_f32_16x16x32_bf16 v[84:87], v[184:187], v[222:225], v[84:87]
	v_mfma_f32_16x16x32_bf16 v[84:87], v[188:191], v[226:229], v[84:87]
	v_mfma_f32_16x16x32_bf16 v[80:83], v[192:195], v[222:225], v[80:83]
	v_mfma_f32_16x16x32_bf16 v[80:83], v[196:199], v[226:229], v[80:83]
	s_setprio 3
	s_barrier
	v_mfma_f32_16x16x32_bf16 v[68:71], v[184:187], v[230:233], v[68:71]
	v_mfma_f32_16x16x32_bf16 v[68:71], v[188:191], v[234:237], v[68:71]
	v_mfma_f32_16x16x32_bf16 v[64:67], v[192:195], v[230:233], v[64:67]
	v_mfma_f32_16x16x32_bf16 v[64:67], v[196:199], v[234:237], v[64:67]
	s_setprio 0
	s_add_i32 s2, s13, s56
	v_lshl_add_u64 v[156:157], v[156:157], 0, s[82:83]
	s_mov_b32 m0, s2
	ds_read_b128 v[200:203], v165 offset:49152
	ds_read_b128 v[210:213], v165 offset:50176
	ds_read_b128 v[214:217], v165 offset:51200
	ds_read_b128 v[218:221], v165 offset:52224
	ds_read_b128 v[222:225], v165 offset:53248
	ds_read_b128 v[226:229], v165 offset:54272
	ds_read_b128 v[230:233], v165 offset:55296
	ds_read_b128 v[234:237], v165 offset:56320
	global_load_lds_dwordx4 v[156:157], off
	s_add_i32 m0, s2, 0x2000
	s_add_u32 s2, s10, 0x40080
	v_lshl_add_u64 v[156:157], v[170:171], 0, s[82:83]
	s_addc_u32 s3, s11, 0
	s_add_i32 s10, s77, s56
	global_load_lds_dwordx4 v[156:157], off
	v_lshl_add_u64 v[156:157], s[2:3], 0, v[174:175]
	s_mov_b32 m0, s10
	s_nop 0
	global_load_lds_dwordx4 v[156:157], off
	v_lshl_add_u64 v[156:157], s[2:3], 0, v[132:133]
	s_add_i32 m0, s10, 0x2000
	s_nop 0
	global_load_lds_dwordx4 v[156:157], off
	v_lshl_add_u64 v[156:157], v[238:239], 0, s[82:83]
	s_mov_b32 m0, s39
	s_nop 0
	global_load_lds_dwordx4 v[156:157], off
	v_lshl_add_u64 v[156:157], v[240:241], 0, s[82:83]
	s_mov_b32 m0, s46
	s_nop 0
	global_load_lds_dwordx4 v[156:157], off
	s_waitcnt vmcnt(8)
	s_waitcnt lgkmcnt(0)
	s_setprio 1
	s_barrier
	v_mfma_f32_16x16x32_bf16 v[60:63], v[144:147], v[200:203], v[60:63]
	v_mfma_f32_16x16x32_bf16 v[60:63], v[148:151], v[210:213], v[60:63]
	v_mfma_f32_16x16x32_bf16 v[56:59], v[152:155], v[200:203], v[56:59]
	v_mfma_f32_16x16x32_bf16 v[56:59], v[166:169], v[210:213], v[56:59]
	v_mfma_f32_16x16x32_bf16 v[44:47], v[144:147], v[214:217], v[44:47]
	v_mfma_f32_16x16x32_bf16 v[44:47], v[148:151], v[218:221], v[44:47]
	v_mfma_f32_16x16x32_bf16 v[40:43], v[152:155], v[214:217], v[40:43]
	v_mfma_f32_16x16x32_bf16 v[40:43], v[166:169], v[218:221], v[40:43]
	v_mfma_f32_16x16x32_bf16 v[28:31], v[144:147], v[222:225], v[28:31]
	v_mfma_f32_16x16x32_bf16 v[28:31], v[148:151], v[226:229], v[28:31]
	v_mfma_f32_16x16x32_bf16 v[24:27], v[152:155], v[222:225], v[24:27]
	v_mfma_f32_16x16x32_bf16 v[24:27], v[166:169], v[226:229], v[24:27]
	v_mfma_f32_16x16x32_bf16 v[12:15], v[144:147], v[230:233], v[12:15]
	v_mfma_f32_16x16x32_bf16 v[12:15], v[148:151], v[234:237], v[12:15]
	v_mfma_f32_16x16x32_bf16 v[8:11], v[152:155], v[230:233], v[8:11]
	v_mfma_f32_16x16x32_bf16 v[8:11], v[166:169], v[234:237], v[8:11]
	v_mfma_f32_16x16x32_bf16 v[52:55], v[184:187], v[200:203], v[52:55]
	v_mfma_f32_16x16x32_bf16 v[52:55], v[188:191], v[210:213], v[52:55]
	v_mfma_f32_16x16x32_bf16 v[48:51], v[192:195], v[200:203], v[48:51]
	v_mfma_f32_16x16x32_bf16 v[48:51], v[196:199], v[210:213], v[48:51]
	v_mfma_f32_16x16x32_bf16 v[36:39], v[184:187], v[214:217], v[36:39]
	v_mfma_f32_16x16x32_bf16 v[36:39], v[188:191], v[218:221], v[36:39]
	v_mfma_f32_16x16x32_bf16 v[32:35], v[192:195], v[214:217], v[32:35]
	v_mfma_f32_16x16x32_bf16 v[32:35], v[196:199], v[218:221], v[32:35]
	v_mfma_f32_16x16x32_bf16 v[20:23], v[184:187], v[222:225], v[20:23]
	v_mfma_f32_16x16x32_bf16 v[20:23], v[188:191], v[226:229], v[20:23]
	v_mfma_f32_16x16x32_bf16 v[16:19], v[192:195], v[222:225], v[16:19]
	v_mfma_f32_16x16x32_bf16 v[16:19], v[196:199], v[226:229], v[16:19]
	s_setprio 3
	s_barrier
	v_mfma_f32_16x16x32_bf16 v[4:7], v[184:187], v[230:233], v[4:7]
	v_mfma_f32_16x16x32_bf16 v[4:7], v[188:191], v[234:237], v[4:7]
	v_mfma_f32_16x16x32_bf16 v[0:3], v[192:195], v[230:233], v[0:3]
	v_mfma_f32_16x16x32_bf16 v[0:3], v[196:199], v[234:237], v[0:3]
	s_setprio 0
	s_add_i32 s12, s12, 2
	s_add_u32 vcc_lo, vcc_lo, 0x100
	s_addc_u32 vcc_hi, vcc_hi, 0
	s_add_u32 s8, s8, 0x100
	s_addc_u32 s9, s9, 0
	s_cmp_gt_u32 s12, 13
	s_cbranch_scc0 .LBB0_242
